# back-edge rotation (loop-carried SALU + LDS address VALU moved in front of the loop-back barrier) in the MLP-up and MLP-down GEMM K-loops
# baseline (speedup 1.0000x reference)
; #define PG8_STAGE(bufoff, gbase, voff) do { _Pragma("unroll") for (int _i = 0; _i < 2; ++_i) \
;         __builtin_amdgcn_global_load_lds((const unsigned*)((const char*)(gbase) + (voff)[_i]), (LAS unsigned*)(lds + (bufoff) + ldsw + _i * 8192), 16, 0, 0); } while (0)
; #define PG8_LDA(dst, b, h) do { _Pragma("unroll") for (int m = 0; m < 4; ++m) _Pragma("unroll") for (int k = 0; k < 2; ++k) dst[m][k] = *(const LAS bf16x8*)(lds + PG8_SA(b, h) + aoff + m * 2048 + k * 1024); } while (0)
; #define PG8_LDB(dst, b, h) do { _Pragma("unroll") for (int n = 0; n < 2; ++n) _Pragma("unroll") for (int k = 0; k < 2; ++k) dst[n][k] = *(const LAS bf16x8*)(lds + PG8_SB(b, h) + boff + n * 2048 + k * 1024); } while (0)
; #define PG8_MMA(ai, bj, At, Bt) do { __builtin_amdgcn_s_setprio(1); _Pragma("unroll") for (int m = 0; m < 4; ++m) _Pragma("unroll") for (int n = 0; n < 2; ++n) _Pragma("unroll") for (int k = 0; k < 2; ++k) \
;         acc[ai][bj][m][n] = __builtin_amdgcn_mfma_f32_16x16x32_bf16(Bt[n][k], At[m][k], acc[ai][bj][m][n], 0, 0, 0); __builtin_amdgcn_s_setprio(0); } while (0)
; #define PG8_WAIT_V(n) asm volatile("s_waitcnt vmcnt(" #n ")" ::: "memory")
; #define PG8_WAIT_L(n) asm volatile("s_waitcnt lgkmcnt(" #n ")" ::: "memory")
; #define PG8_BAR __builtin_amdgcn_s_barrier()
; #define PG8_SCHED __builtin_amdgcn_sched_barrier(0)
; template <class Epi, class Sched, bool ALIGN_EPI>
; __device__ __forceinline__ void gemm_phase(LAS unsigned char* lds, const Gemm g, const Sched& S, const Epi& E, int wave_s) {
;     ...
;             PG8_LDB(B0, 0, 0); PG8_LDB(B1, 0, 1); PG8_SCHED; PG8_LDA(At, 0, 0); PG8_STAGE(PG8_SA(1, 1), a1 + hstepA, voffA);
;             PG8_WAIT_V(8); PG8_WAIT_L(0); PG8_BAR; PG8_MMA(0, 0, At, B0); PG8_MMA(0, 1, At, B1); PG8_BAR; PG8_SCHED;
;             PG8_LDA(At, 0, 1); PG8_STAGE(PG8_SB(0, 0), b2, voffB); PG8_STAGE(PG8_SB(0, 1), b2 + hstepB, voffB); PG8_STAGE(PG8_SA(0, 0), a2, voffA);
;             PG8_WAIT_V(8); PG8_WAIT_L(0); PG8_BAR; PG8_MMA(1, 0, At, B0); PG8_MMA(1, 1, At, B1); PG8_BAR; PG8_SCHED;
.Lgemm_mlpup_head:
	ds_read_b128 v[130:133], v142
	ds_read_b128 v[134:137], v142 offset:1024
	ds_read_b128 v[138:141], v142 offset:2048
	ds_read_b128 v[142:145], v142 offset:3072
	ds_read_b128 v[158:161], v170
	ds_read_b128 v[162:165], v170 offset:1024
	ds_read_b128 v[166:169], v170 offset:2048
	ds_read_b128 v[170:173], v170 offset:3072
	v_lshl_add_u64 v[208:209], s[34:35], 0, v[154:155]
	s_add_i32 m0, s31, 0xc000
	ds_read_b128 v[176:179], v174
	ds_read_b128 v[180:183], v174 offset:1024
	ds_read_b128 v[184:187], v174 offset:2048
	ds_read_b128 v[188:191], v174 offset:3072
	ds_read_b128 v[192:195], v174 offset:4096
	ds_read_b128 v[196:199], v174 offset:5120
	ds_read_b128 v[200:203], v174 offset:6144
	ds_read_b128 v[204:207], v174 offset:7168
	global_load_lds_dwordx4 v[208:209], off
	v_lshl_add_u64 v[208:209], s[34:35], 0, v[156:157]
	s_add_i32 m0, s31, 0xe000
	s_nop 0
	global_load_lds_dwordx4 v[208:209], off
	s_waitcnt vmcnt(8)
	s_waitcnt lgkmcnt(0)
	s_barrier
	s_setprio 1
	s_waitcnt lgkmcnt(0)
	v_mfma_f32_16x16x32_bf16 v[126:129], v[130:133], v[176:179], v[126:129]
	v_mfma_f32_16x16x32_bf16 v[122:125], v[138:141], v[176:179], v[122:125]
	v_mfma_f32_16x16x32_bf16 v[110:113], v[130:133], v[184:187], v[110:113]
	v_mfma_f32_16x16x32_bf16 v[106:109], v[138:141], v[184:187], v[106:109]
	v_mfma_f32_16x16x32_bf16 v[94:97], v[130:133], v[192:195], v[94:97]
	v_mfma_f32_16x16x32_bf16 v[90:93], v[138:141], v[192:195], v[90:93]
	v_mfma_f32_16x16x32_bf16 v[78:81], v[130:133], v[200:203], v[78:81]
	v_mfma_f32_16x16x32_bf16 v[74:77], v[138:141], v[200:203], v[74:77]
	v_mfma_f32_16x16x32_bf16 v[126:129], v[134:137], v[180:183], v[126:129]
	v_mfma_f32_16x16x32_bf16 v[122:125], v[142:145], v[180:183], v[122:125]
	v_mfma_f32_16x16x32_bf16 v[110:113], v[134:137], v[188:191], v[110:113]
	v_mfma_f32_16x16x32_bf16 v[106:109], v[142:145], v[188:191], v[106:109]
	v_mfma_f32_16x16x32_bf16 v[94:97], v[134:137], v[196:199], v[94:97]
	v_mfma_f32_16x16x32_bf16 v[90:93], v[142:145], v[196:199], v[90:93]
	v_mfma_f32_16x16x32_bf16 v[78:81], v[134:137], v[204:207], v[78:81]
	v_mfma_f32_16x16x32_bf16 v[74:77], v[142:145], v[204:207], v[74:77]
	s_setprio 0
	s_setprio 1
	v_mfma_f32_16x16x32_bf16 v[118:121], v[158:161], v[176:179], v[118:121]
	v_mfma_f32_16x16x32_bf16 v[114:117], v[166:169], v[176:179], v[114:117]
	v_mfma_f32_16x16x32_bf16 v[102:105], v[158:161], v[184:187], v[102:105]
	v_mfma_f32_16x16x32_bf16 v[98:101], v[166:169], v[184:187], v[98:101]
	v_mfma_f32_16x16x32_bf16 v[86:89], v[158:161], v[192:195], v[86:89]
	v_mfma_f32_16x16x32_bf16 v[82:85], v[166:169], v[192:195], v[82:85]
	v_mfma_f32_16x16x32_bf16 v[70:73], v[158:161], v[200:203], v[70:73]
	v_mfma_f32_16x16x32_bf16 v[66:69], v[166:169], v[200:203], v[66:69]
	v_mfma_f32_16x16x32_bf16 v[118:121], v[162:165], v[180:183], v[118:121]
	v_mfma_f32_16x16x32_bf16 v[114:117], v[170:173], v[180:183], v[114:117]
	v_mfma_f32_16x16x32_bf16 v[102:105], v[162:165], v[188:191], v[102:105]
	v_mfma_f32_16x16x32_bf16 v[98:101], v[170:173], v[188:191], v[98:101]
	v_mfma_f32_16x16x32_bf16 v[86:89], v[162:165], v[196:199], v[86:89]
	v_mfma_f32_16x16x32_bf16 v[82:85], v[170:173], v[196:199], v[82:85]
	v_mfma_f32_16x16x32_bf16 v[70:73], v[162:165], v[204:207], v[70:73]
	v_mfma_f32_16x16x32_bf16 v[66:69], v[170:173], v[204:207], v[66:69]
	s_setprio 0
	s_barrier
	s_add_i32 s5, s95, s43
	v_lshl_add_u64 v[208:209], s[36:37], 0, v[150:151]
	s_mov_b32 m0, s5
	ds_read_b128 v[176:179], v174 offset:16384
	ds_read_b128 v[180:183], v174 offset:17408
	ds_read_b128 v[184:187], v174 offset:18432
	ds_read_b128 v[188:191], v174 offset:19456
	ds_read_b128 v[192:195], v174 offset:20480
	ds_read_b128 v[196:199], v174 offset:21504
	ds_read_b128 v[200:203], v174 offset:22528
	ds_read_b128 v[204:207], v174 offset:23552
	global_load_lds_dwordx4 v[208:209], off
	s_add_i32 m0, s5, 0x2000
	s_add_u32 vcc_lo, s36, 0x40000
	v_lshl_add_u64 v[210:211], s[36:37], 0, v[146:147]
	s_addc_u32 vcc_hi, s37, 0
	s_add_i32 s4, s4, s43
	global_load_lds_dwordx4 v[210:211], off
	v_lshl_add_u64 v[212:213], vcc, 0, v[150:151]
	s_mov_b32 m0, s4
	v_lshl_add_u64 v[214:215], s[38:39], 0, v[148:149]
	global_load_lds_dwordx4 v[212:213], off
	v_lshl_add_u64 v[212:213], vcc, 0, v[146:147]
	s_add_i32 m0, s4, 0x2000
	s_nop 0
	global_load_lds_dwordx4 v[212:213], off
	v_lshl_add_u64 v[212:213], s[38:39], 0, v[152:153]
	s_mov_b32 m0, s31
	s_nop 0
	global_load_lds_dwordx4 v[212:213], off
	s_mov_b32 m0, s82
	s_nop 0
	global_load_lds_dwordx4 v[214:215], off
	s_waitcnt vmcnt(8)
	s_waitcnt lgkmcnt(0)
	s_barrier
; #define PG8_STAGE(bufoff, gbase, voff) do { _Pragma("unroll") for (int _i = 0; _i < 2; ++_i) \
;         __builtin_amdgcn_global_load_lds((const unsigned*)((const char*)(gbase) + (voff)[_i]), (LAS unsigned*)(lds + (bufoff) + ldsw + _i * 8192), 16, 0, 0); } while (0)
; #define PG8_LDA(dst, b, h) do { _Pragma("unroll") for (int m = 0; m < 4; ++m) _Pragma("unroll") for (int k = 0; k < 2; ++k) dst[m][k] = *(const LAS bf16x8*)(lds + PG8_SA(b, h) + aoff + m * 2048 + k * 1024); } while (0)
; #define PG8_LDB(dst, b, h) do { _Pragma("unroll") for (int n = 0; n < 2; ++n) _Pragma("unroll") for (int k = 0; k < 2; ++k) dst[n][k] = *(const LAS bf16x8*)(lds + PG8_SB(b, h) + boff + n * 2048 + k * 1024); } while (0)
; #define PG8_MMA(ai, bj, At, Bt) do { __builtin_amdgcn_s_setprio(1); _Pragma("unroll") for (int m = 0; m < 4; ++m) _Pragma("unroll") for (int n = 0; n < 2; ++n) _Pragma("unroll") for (int k = 0; k < 2; ++k) \
;         acc[ai][bj][m][n] = __builtin_amdgcn_mfma_f32_16x16x32_bf16(Bt[n][k], At[m][k], acc[ai][bj][m][n], 0, 0, 0); __builtin_amdgcn_s_setprio(0); } while (0)
; #define PG8_WAIT_V(n) asm volatile("s_waitcnt vmcnt(" #n ")" ::: "memory")
; #define PG8_WAIT_L(n) asm volatile("s_waitcnt lgkmcnt(" #n ")" ::: "memory")
; #define PG8_BAR __builtin_amdgcn_s_barrier()
; #define PG8_SCHED __builtin_amdgcn_sched_barrier(0)
; template <class Epi, class Sched, bool ALIGN_EPI>
; __device__ __forceinline__ void gemm_phase(LAS unsigned char* lds, const Gemm g, const Sched& S, const Epi& E, int wave_s) {
;     ...
;             PG8_WAIT_V(8); PG8_WAIT_L(0); PG8_BAR; PG8_MMA(1, 0, At, B0); PG8_MMA(1, 1, At, B1); PG8_BAR; PG8_SCHED;
;             PG8_LDB(B0, 1, 0); PG8_LDB(B1, 1, 1); PG8_SCHED; PG8_LDA(At, 1, 0); PG8_STAGE(PG8_SA(0, 1), a2 + hstepA, voffA);
;             PG8_WAIT_V(8); PG8_WAIT_L(0); PG8_BAR; PG8_MMA(0, 0, At, B0); PG8_MMA(0, 1, At, B1); PG8_BAR; PG8_SCHED;
	s_setprio 1
	s_waitcnt lgkmcnt(0)
	v_mfma_f32_16x16x32_bf16 v[62:65], v[130:133], v[176:179], v[62:65]
	v_mfma_f32_16x16x32_bf16 v[58:61], v[138:141], v[176:179], v[58:61]
	v_mfma_f32_16x16x32_bf16 v[46:49], v[130:133], v[184:187], v[46:49]
	v_mfma_f32_16x16x32_bf16 v[42:45], v[138:141], v[184:187], v[42:45]
	v_mfma_f32_16x16x32_bf16 v[30:33], v[130:133], v[192:195], v[30:33]
	v_mfma_f32_16x16x32_bf16 v[26:29], v[138:141], v[192:195], v[26:29]
	v_mfma_f32_16x16x32_bf16 v[14:17], v[130:133], v[200:203], v[14:17]
	v_mfma_f32_16x16x32_bf16 v[10:13], v[138:141], v[200:203], v[10:13]
	v_mfma_f32_16x16x32_bf16 v[62:65], v[134:137], v[180:183], v[62:65]
	v_mfma_f32_16x16x32_bf16 v[58:61], v[142:145], v[180:183], v[58:61]
	v_mfma_f32_16x16x32_bf16 v[46:49], v[134:137], v[188:191], v[46:49]
	v_mfma_f32_16x16x32_bf16 v[42:45], v[142:145], v[188:191], v[42:45]
	v_mfma_f32_16x16x32_bf16 v[30:33], v[134:137], v[196:199], v[30:33]
	v_mfma_f32_16x16x32_bf16 v[26:29], v[142:145], v[196:199], v[26:29]
	v_mfma_f32_16x16x32_bf16 v[14:17], v[134:137], v[204:207], v[14:17]
	v_mfma_f32_16x16x32_bf16 v[10:13], v[142:145], v[204:207], v[10:13]
	s_setprio 0
	s_setprio 1
	v_mfma_f32_16x16x32_bf16 v[54:57], v[158:161], v[176:179], v[54:57]
	v_mfma_f32_16x16x32_bf16 v[50:53], v[166:169], v[176:179], v[50:53]
	v_mfma_f32_16x16x32_bf16 v[38:41], v[158:161], v[184:187], v[38:41]
	v_mfma_f32_16x16x32_bf16 v[34:37], v[166:169], v[184:187], v[34:37]
	v_mfma_f32_16x16x32_bf16 v[22:25], v[158:161], v[192:195], v[22:25]
	v_mfma_f32_16x16x32_bf16 v[18:21], v[166:169], v[192:195], v[18:21]
	v_mfma_f32_16x16x32_bf16 v[6:9], v[158:161], v[200:203], v[6:9]
	v_mfma_f32_16x16x32_bf16 v[2:5], v[166:169], v[200:203], v[2:5]
	v_mfma_f32_16x16x32_bf16 v[54:57], v[162:165], v[180:183], v[54:57]
	v_mfma_f32_16x16x32_bf16 v[50:53], v[170:173], v[180:183], v[50:53]
	v_mfma_f32_16x16x32_bf16 v[38:41], v[162:165], v[188:191], v[38:41]
	v_mfma_f32_16x16x32_bf16 v[34:37], v[170:173], v[188:191], v[34:37]
	v_mfma_f32_16x16x32_bf16 v[22:25], v[162:165], v[196:199], v[22:25]
	v_mfma_f32_16x16x32_bf16 v[18:21], v[170:173], v[196:199], v[18:21]
	v_mfma_f32_16x16x32_bf16 v[6:9], v[162:165], v[204:207], v[6:9]
	v_mfma_f32_16x16x32_bf16 v[2:5], v[170:173], v[204:207], v[2:5]
	s_setprio 0
	s_barrier
	s_add_i32 s4, 0, 0x18000
	s_add_i32 s5, 0, 0x1c000
	v_add_u32_e32 v142, s4, v1
	v_add_u32_e32 v170, s5, v1
	ds_read_b128 v[130:133], v142
	ds_read_b128 v[134:137], v142 offset:1024
	ds_read_b128 v[138:141], v142 offset:2048
	ds_read_b128 v[142:145], v142 offset:3072
	ds_read_b128 v[158:161], v170
	ds_read_b128 v[162:165], v170 offset:1024
	ds_read_b128 v[166:169], v170 offset:2048
	ds_read_b128 v[170:173], v170 offset:3072
	s_add_u32 s38, s38, 0x40000
	s_addc_u32 s39, s39, 0
	s_mov_b32 m0, s83
	v_lshl_add_u64 v[216:217], s[38:39], 0, v[152:153]
	ds_read_b128 v[176:179], v174 offset:32768
	ds_read_b128 v[180:183], v174 offset:33792
	ds_read_b128 v[184:187], v174 offset:34816
	ds_read_b128 v[188:191], v174 offset:35840
	ds_read_b128 v[192:195], v174 offset:36864
	ds_read_b128 v[196:199], v174 offset:37888
	ds_read_b128 v[200:203], v174 offset:38912
	ds_read_b128 v[204:207], v174 offset:39936
	global_load_lds_dwordx4 v[216:217], off
	v_lshl_add_u64 v[216:217], s[38:39], 0, v[148:149]
	s_mov_b32 m0, s84
	s_nop 0
	global_load_lds_dwordx4 v[216:217], off
	s_waitcnt vmcnt(8)
	s_waitcnt lgkmcnt(0)
	s_barrier
	s_setprio 1
	s_waitcnt lgkmcnt(0)
	v_mfma_f32_16x16x32_bf16 v[126:129], v[130:133], v[176:179], v[126:129]
	v_mfma_f32_16x16x32_bf16 v[122:125], v[138:141], v[176:179], v[122:125]
	v_mfma_f32_16x16x32_bf16 v[110:113], v[130:133], v[184:187], v[110:113]
	v_mfma_f32_16x16x32_bf16 v[106:109], v[138:141], v[184:187], v[106:109]
	v_mfma_f32_16x16x32_bf16 v[94:97], v[130:133], v[192:195], v[94:97]
	v_mfma_f32_16x16x32_bf16 v[90:93], v[138:141], v[192:195], v[90:93]
	v_mfma_f32_16x16x32_bf16 v[78:81], v[130:133], v[200:203], v[78:81]
	v_mfma_f32_16x16x32_bf16 v[74:77], v[138:141], v[200:203], v[74:77]
	v_mfma_f32_16x16x32_bf16 v[126:129], v[134:137], v[180:183], v[126:129]
	v_mfma_f32_16x16x32_bf16 v[122:125], v[142:145], v[180:183], v[122:125]
	v_mfma_f32_16x16x32_bf16 v[110:113], v[134:137], v[188:191], v[110:113]
	v_mfma_f32_16x16x32_bf16 v[106:109], v[142:145], v[188:191], v[106:109]
	v_mfma_f32_16x16x32_bf16 v[94:97], v[134:137], v[196:199], v[94:97]
	v_mfma_f32_16x16x32_bf16 v[90:93], v[142:145], v[196:199], v[90:93]
	v_mfma_f32_16x16x32_bf16 v[78:81], v[134:137], v[204:207], v[78:81]
	v_mfma_f32_16x16x32_bf16 v[74:77], v[142:145], v[204:207], v[74:77]
	s_setprio 0
	s_setprio 1
	v_mfma_f32_16x16x32_bf16 v[118:121], v[158:161], v[176:179], v[118:121]
	v_mfma_f32_16x16x32_bf16 v[114:117], v[166:169], v[176:179], v[114:117]
	v_mfma_f32_16x16x32_bf16 v[102:105], v[158:161], v[184:187], v[102:105]
	v_mfma_f32_16x16x32_bf16 v[98:101], v[166:169], v[184:187], v[98:101]
	v_mfma_f32_16x16x32_bf16 v[86:89], v[158:161], v[192:195], v[86:89]
	v_mfma_f32_16x16x32_bf16 v[82:85], v[166:169], v[192:195], v[82:85]
	v_mfma_f32_16x16x32_bf16 v[70:73], v[158:161], v[200:203], v[70:73]
	v_mfma_f32_16x16x32_bf16 v[66:69], v[166:169], v[200:203], v[66:69]
	v_mfma_f32_16x16x32_bf16 v[118:121], v[162:165], v[180:183], v[118:121]
	v_mfma_f32_16x16x32_bf16 v[114:117], v[170:173], v[180:183], v[114:117]
	v_mfma_f32_16x16x32_bf16 v[102:105], v[162:165], v[188:191], v[102:105]
	v_mfma_f32_16x16x32_bf16 v[98:101], v[170:173], v[188:191], v[98:101]
	v_mfma_f32_16x16x32_bf16 v[86:89], v[162:165], v[196:199], v[86:89]
	v_mfma_f32_16x16x32_bf16 v[82:85], v[170:173], v[196:199], v[82:85]
	v_mfma_f32_16x16x32_bf16 v[70:73], v[162:165], v[204:207], v[70:73]
	v_mfma_f32_16x16x32_bf16 v[66:69], v[170:173], v[204:207], v[66:69]
	s_setprio 0
	s_barrier
; #define PG8_STAGE(bufoff, gbase, voff) do { _Pragma("unroll") for (int _i = 0; _i < 2; ++_i) \
;         __builtin_amdgcn_global_load_lds((const unsigned*)((const char*)(gbase) + (voff)[_i]), (LAS unsigned*)(lds + (bufoff) + ldsw + _i * 8192), 16, 0, 0); } while (0)
; #define PG8_LDA(dst, b, h) do { _Pragma("unroll") for (int m = 0; m < 4; ++m) _Pragma("unroll") for (int k = 0; k < 2; ++k) dst[m][k] = *(const LAS bf16x8*)(lds + PG8_SA(b, h) + aoff + m * 2048 + k * 1024); } while (0)
; #define PG8_MMA(ai, bj, At, Bt) do { __builtin_amdgcn_s_setprio(1); _Pragma("unroll") for (int m = 0; m < 4; ++m) _Pragma("unroll") for (int n = 0; n < 2; ++n) _Pragma("unroll") for (int k = 0; k < 2; ++k) \
;         acc[ai][bj][m][n] = __builtin_amdgcn_mfma_f32_16x16x32_bf16(Bt[n][k], At[m][k], acc[ai][bj][m][n], 0, 0, 0); __builtin_amdgcn_s_setprio(0); } while (0)
; #define PG8_WAIT_V(n) asm volatile("s_waitcnt vmcnt(" #n ")" ::: "memory")
; #define PG8_WAIT_L(n) asm volatile("s_waitcnt lgkmcnt(" #n ")" ::: "memory")
; #define PG8_BAR __builtin_amdgcn_s_barrier()
; #define PG8_SCHED __builtin_amdgcn_sched_barrier(0)
; template <class Epi, class Sched, bool ALIGN_EPI>
; __device__ __forceinline__ void gemm_phase(LAS unsigned char* lds, const Gemm g, const Sched& S, const Epi& E, int wave_s) {
;     ...
;         for (int t = 0; t < nt; t += 2) {
;             const bool last = (t == nt - 2);
;             const char* a1 = cA + (size_t)(t + 1) * kstep;
;             const char* a2 = last ? nA : cA + (size_t)(t + 2) * kstep; const char* b2 = last ? nB : cB + (size_t)(t + 2) * kstep;
;             const char* a3 = a2 + kstep; const char* b3 = b2 + kstep;
;     ...
;             PG8_WAIT_V(8); PG8_WAIT_L(0); PG8_BAR; PG8_MMA(0, 0, At, B0); PG8_MMA(0, 1, At, B1); PG8_BAR; PG8_SCHED;
;             PG8_LDA(At, 1, 1); PG8_STAGE(PG8_SB(1, 0), b3, voffB); PG8_STAGE(PG8_SB(1, 1), b3 + hstepB, voffB); PG8_STAGE(PG8_SA(1, 0), a3, voffA);
;             PG8_WAIT_V(8); PG8_WAIT_L(0); PG8_BAR; PG8_MMA(1, 0, At, B0); PG8_MMA(1, 1, At, B1); PG8_BAR; PG8_SCHED;
	s_add_i32 s4, s4, s43
	v_lshl_add_u64 v[208:209], v[208:209], 0, s[74:75]
	s_mov_b32 m0, s4
	ds_read_b128 v[176:179], v174 offset:49152
	ds_read_b128 v[180:183], v174 offset:50176
	ds_read_b128 v[184:187], v174 offset:51200
	ds_read_b128 v[188:191], v174 offset:52224
	ds_read_b128 v[192:195], v174 offset:53248
	ds_read_b128 v[196:199], v174 offset:54272
	ds_read_b128 v[200:203], v174 offset:55296
	ds_read_b128 v[204:207], v174 offset:56320
	global_load_lds_dwordx4 v[208:209], off
	s_add_i32 m0, s4, 0x2000
	s_add_u32 s36, s36, 0x40080
	v_lshl_add_u64 v[208:209], v[210:211], 0, s[74:75]
	s_addc_u32 s37, s37, 0
	s_add_i32 s4, s5, s43
	global_load_lds_dwordx4 v[208:209], off
	v_lshl_add_u64 v[208:209], s[36:37], 0, v[150:151]
	s_mov_b32 m0, s4
	s_nop 0
	global_load_lds_dwordx4 v[208:209], off
	v_lshl_add_u64 v[208:209], s[36:37], 0, v[146:147]
	s_add_i32 m0, s4, 0x2000
	s_nop 0
	global_load_lds_dwordx4 v[208:209], off
	v_lshl_add_u64 v[208:209], v[212:213], 0, s[74:75]
	s_mov_b32 m0, s88
	s_nop 0
	global_load_lds_dwordx4 v[208:209], off
	v_lshl_add_u64 v[208:209], v[214:215], 0, s[74:75]
	s_mov_b32 m0, s89
	s_nop 0
	global_load_lds_dwordx4 v[208:209], off
	s_waitcnt vmcnt(8)
	s_waitcnt lgkmcnt(0)
	s_barrier
	s_setprio 1
	s_waitcnt lgkmcnt(0)
	v_mfma_f32_16x16x32_bf16 v[62:65], v[130:133], v[176:179], v[62:65]
	v_mfma_f32_16x16x32_bf16 v[58:61], v[138:141], v[176:179], v[58:61]
	v_mfma_f32_16x16x32_bf16 v[46:49], v[130:133], v[184:187], v[46:49]
	v_mfma_f32_16x16x32_bf16 v[42:45], v[138:141], v[184:187], v[42:45]
	v_mfma_f32_16x16x32_bf16 v[30:33], v[130:133], v[192:195], v[30:33]
	v_mfma_f32_16x16x32_bf16 v[26:29], v[138:141], v[192:195], v[26:29]
	v_mfma_f32_16x16x32_bf16 v[14:17], v[130:133], v[200:203], v[14:17]
	v_mfma_f32_16x16x32_bf16 v[10:13], v[138:141], v[200:203], v[10:13]
	v_mfma_f32_16x16x32_bf16 v[62:65], v[134:137], v[180:183], v[62:65]
	v_mfma_f32_16x16x32_bf16 v[58:61], v[142:145], v[180:183], v[58:61]
	v_mfma_f32_16x16x32_bf16 v[46:49], v[134:137], v[188:191], v[46:49]
	v_mfma_f32_16x16x32_bf16 v[42:45], v[142:145], v[188:191], v[42:45]
	v_mfma_f32_16x16x32_bf16 v[30:33], v[134:137], v[196:199], v[30:33]
	v_mfma_f32_16x16x32_bf16 v[26:29], v[142:145], v[196:199], v[26:29]
	v_mfma_f32_16x16x32_bf16 v[14:17], v[134:137], v[204:207], v[14:17]
	v_mfma_f32_16x16x32_bf16 v[10:13], v[142:145], v[204:207], v[10:13]
	s_setprio 0
	s_setprio 1
	v_mfma_f32_16x16x32_bf16 v[54:57], v[158:161], v[176:179], v[54:57]
	v_mfma_f32_16x16x32_bf16 v[50:53], v[166:169], v[176:179], v[50:53]
	v_mfma_f32_16x16x32_bf16 v[38:41], v[158:161], v[184:187], v[38:41]
	v_mfma_f32_16x16x32_bf16 v[34:37], v[166:169], v[184:187], v[34:37]
	v_mfma_f32_16x16x32_bf16 v[22:25], v[158:161], v[192:195], v[22:25]
	v_mfma_f32_16x16x32_bf16 v[18:21], v[166:169], v[192:195], v[18:21]
	v_mfma_f32_16x16x32_bf16 v[6:9], v[158:161], v[200:203], v[6:9]
	v_mfma_f32_16x16x32_bf16 v[2:5], v[166:169], v[200:203], v[2:5]
	v_mfma_f32_16x16x32_bf16 v[54:57], v[162:165], v[180:183], v[54:57]
	v_mfma_f32_16x16x32_bf16 v[50:53], v[170:173], v[180:183], v[50:53]
	v_mfma_f32_16x16x32_bf16 v[38:41], v[162:165], v[188:191], v[38:41]
	v_mfma_f32_16x16x32_bf16 v[34:37], v[170:173], v[188:191], v[34:37]
	v_mfma_f32_16x16x32_bf16 v[22:25], v[162:165], v[196:199], v[22:25]
	v_mfma_f32_16x16x32_bf16 v[18:21], v[170:173], v[196:199], v[18:21]
	v_mfma_f32_16x16x32_bf16 v[6:9], v[162:165], v[204:207], v[6:9]
	v_mfma_f32_16x16x32_bf16 v[2:5], v[170:173], v[204:207], v[2:5]
	s_setprio 0
	s_add_i32 s94, s94, 2
	s_add_u32 s34, s34, 0x100
	s_addc_u32 s35, s35, 0
	s_add_u32 s92, s92, 0x100
	s_addc_u32 s93, s93, 0
	s_cmp_gt_u32 s94, 13
	s_cbranch_scc1 .Lgemm_mlpup_exit
	s_add_u32 s36, s34, 0xfffc0080
	s_addc_u32 s37, s35, -1
	s_add_i32 s95, 0, 0x10000
	s_cmp_eq_u32 s94, 12
	s_cselect_b32 s39, s23, s37
	s_cselect_b32 s38, s29, s36
	s_cselect_b32 s37, s21, s93
	s_cselect_b32 s36, s91, s92
	s_add_i32 s4, 0, 0x14000
	v_add_u32_e32 v142, s95, v1
	v_add_u32_e32 v170, s4, v1
	s_barrier
	s_branch .Lgemm_mlpup_head
.Lgemm_mlpup_exit:
	s_barrier
	s_and_b64 vcc, exec, s[78:79]
	s_cbranch_vccz .LBB0_1493
	s_barrier

; #define PG8_STAGE(bufoff, gbase, voff) do { _Pragma("unroll") for (int _i = 0; _i < 2; ++_i) \
;         __builtin_amdgcn_global_load_lds((const unsigned*)((const char*)(gbase) + (voff)[_i]), (LAS unsigned*)(lds + (bufoff) + ldsw + _i * 8192), 16, 0, 0); } while (0)
; #define PG8_LDA(dst, b, h) do { _Pragma("unroll") for (int m = 0; m < 4; ++m) _Pragma("unroll") for (int k = 0; k < 2; ++k) dst[m][k] = *(const LAS bf16x8*)(lds + PG8_SA(b, h) + aoff + m * 2048 + k * 1024); } while (0)
; #define PG8_LDB(dst, b, h) do { _Pragma("unroll") for (int n = 0; n < 2; ++n) _Pragma("unroll") for (int k = 0; k < 2; ++k) dst[n][k] = *(const LAS bf16x8*)(lds + PG8_SB(b, h) + boff + n * 2048 + k * 1024); } while (0)
; #define PG8_MMA(ai, bj, At, Bt) do { __builtin_amdgcn_s_setprio(1); _Pragma("unroll") for (int m = 0; m < 4; ++m) _Pragma("unroll") for (int n = 0; n < 2; ++n) _Pragma("unroll") for (int k = 0; k < 2; ++k) \
;         acc[ai][bj][m][n] = __builtin_amdgcn_mfma_f32_16x16x32_bf16(Bt[n][k], At[m][k], acc[ai][bj][m][n], 0, 0, 0); __builtin_amdgcn_s_setprio(0); } while (0)
; #define PG8_WAIT_V(n) asm volatile("s_waitcnt vmcnt(" #n ")" ::: "memory")
; #define PG8_WAIT_L(n) asm volatile("s_waitcnt lgkmcnt(" #n ")" ::: "memory")
; #define PG8_BAR __builtin_amdgcn_s_barrier()
; #define PG8_SCHED __builtin_amdgcn_sched_barrier(0)
; template <class Epi, class Sched, bool ALIGN_EPI>
; __device__ __forceinline__ void gemm_phase(LAS unsigned char* lds, const Gemm g, const Sched& S, const Epi& E, int wave_s) {
;     ...
;             PG8_LDB(B0, 0, 0); PG8_LDB(B1, 0, 1); PG8_SCHED; PG8_LDA(At, 0, 0); PG8_STAGE(PG8_SA(1, 1), a1 + hstepA, voffA);
;             PG8_WAIT_V(8); PG8_WAIT_L(0); PG8_BAR; PG8_MMA(0, 0, At, B0); PG8_MMA(0, 1, At, B1); PG8_BAR; PG8_SCHED;
;             PG8_LDA(At, 0, 1); PG8_STAGE(PG8_SB(0, 0), b2, voffB); PG8_STAGE(PG8_SB(0, 1), b2 + hstepB, voffB); PG8_STAGE(PG8_SA(0, 0), a2, voffA);
;             PG8_WAIT_V(8); PG8_WAIT_L(0); PG8_BAR; PG8_MMA(1, 0, At, B0); PG8_MMA(1, 1, At, B1); PG8_BAR; PG8_SCHED;
.Lgemm_mlpdn_head:
	ds_read_b128 v[66:69], v78
	ds_read_b128 v[70:73], v78 offset:1024
	ds_read_b128 v[74:77], v78 offset:2048
	ds_read_b128 v[78:81], v78 offset:3072
	ds_read_b128 v[146:149], v170
	ds_read_b128 v[150:153], v170 offset:1024
	ds_read_b128 v[154:157], v170 offset:2048
	ds_read_b128 v[170:173], v170 offset:3072
	v_lshl_add_u64 v[208:209], s[10:11], 0, v[166:167]
	s_add_i32 m0, s39, 0xc000
	ds_read_b128 v[174:177], v198
	ds_read_b128 v[178:181], v198 offset:1024
	ds_read_b128 v[182:185], v198 offset:2048
	ds_read_b128 v[186:189], v198 offset:3072
	ds_read_b128 v[190:193], v198 offset:4096
	ds_read_b128 v[194:197], v198 offset:5120
	ds_read_b128 v[200:203], v198 offset:6144
	ds_read_b128 v[204:207], v198 offset:7168
	global_load_lds_dwordx4 v[208:209], off
	v_lshl_add_u64 v[208:209], s[10:11], 0, v[168:169]
	s_add_i32 m0, s39, 0xe000
	s_nop 0
	global_load_lds_dwordx4 v[208:209], off
	s_waitcnt vmcnt(8)
	s_waitcnt lgkmcnt(0)
	s_barrier
	s_setprio 1
	s_waitcnt lgkmcnt(0)
	v_mfma_f32_16x16x32_bf16 v[142:145], v[66:69], v[174:177], v[142:145]
	v_mfma_f32_16x16x32_bf16 v[138:141], v[74:77], v[174:177], v[138:141]
	v_mfma_f32_16x16x32_bf16 v[126:129], v[66:69], v[182:185], v[126:129]
	v_mfma_f32_16x16x32_bf16 v[122:125], v[74:77], v[182:185], v[122:125]
	v_mfma_f32_16x16x32_bf16 v[110:113], v[66:69], v[190:193], v[110:113]
	v_mfma_f32_16x16x32_bf16 v[106:109], v[74:77], v[190:193], v[106:109]
	v_mfma_f32_16x16x32_bf16 v[94:97], v[66:69], v[200:203], v[94:97]
	v_mfma_f32_16x16x32_bf16 v[90:93], v[74:77], v[200:203], v[90:93]
	v_mfma_f32_16x16x32_bf16 v[142:145], v[70:73], v[178:181], v[142:145]
	v_mfma_f32_16x16x32_bf16 v[138:141], v[78:81], v[178:181], v[138:141]
	v_mfma_f32_16x16x32_bf16 v[126:129], v[70:73], v[186:189], v[126:129]
	v_mfma_f32_16x16x32_bf16 v[122:125], v[78:81], v[186:189], v[122:125]
	v_mfma_f32_16x16x32_bf16 v[110:113], v[70:73], v[194:197], v[110:113]
	v_mfma_f32_16x16x32_bf16 v[106:109], v[78:81], v[194:197], v[106:109]
	v_mfma_f32_16x16x32_bf16 v[94:97], v[70:73], v[204:207], v[94:97]
	v_mfma_f32_16x16x32_bf16 v[90:93], v[78:81], v[204:207], v[90:93]
	s_setprio 0
	s_setprio 1
	v_mfma_f32_16x16x32_bf16 v[134:137], v[146:149], v[174:177], v[134:137]
	v_mfma_f32_16x16x32_bf16 v[130:133], v[154:157], v[174:177], v[130:133]
	v_mfma_f32_16x16x32_bf16 v[118:121], v[146:149], v[182:185], v[118:121]
	v_mfma_f32_16x16x32_bf16 v[114:117], v[154:157], v[182:185], v[114:117]
	v_mfma_f32_16x16x32_bf16 v[102:105], v[146:149], v[190:193], v[102:105]
	v_mfma_f32_16x16x32_bf16 v[98:101], v[154:157], v[190:193], v[98:101]
	v_mfma_f32_16x16x32_bf16 v[86:89], v[146:149], v[200:203], v[86:89]
	v_mfma_f32_16x16x32_bf16 v[82:85], v[154:157], v[200:203], v[82:85]
	v_mfma_f32_16x16x32_bf16 v[134:137], v[150:153], v[178:181], v[134:137]
	v_mfma_f32_16x16x32_bf16 v[130:133], v[170:173], v[178:181], v[130:133]
	v_mfma_f32_16x16x32_bf16 v[118:121], v[150:153], v[186:189], v[118:121]
	v_mfma_f32_16x16x32_bf16 v[114:117], v[170:173], v[186:189], v[114:117]
	v_mfma_f32_16x16x32_bf16 v[102:105], v[150:153], v[194:197], v[102:105]
	v_mfma_f32_16x16x32_bf16 v[98:101], v[170:173], v[194:197], v[98:101]
	v_mfma_f32_16x16x32_bf16 v[86:89], v[150:153], v[204:207], v[86:89]
	v_mfma_f32_16x16x32_bf16 v[82:85], v[170:173], v[204:207], v[82:85]
	s_setprio 0
	s_barrier
	s_add_i32 s7, s95, s38
	v_lshl_add_u64 v[208:209], s[30:31], 0, v[162:163]
	s_mov_b32 m0, s7
	ds_read_b128 v[174:177], v198 offset:16384
	ds_read_b128 v[178:181], v198 offset:17408
	ds_read_b128 v[182:185], v198 offset:18432
	ds_read_b128 v[186:189], v198 offset:19456
	ds_read_b128 v[190:193], v198 offset:20480
	ds_read_b128 v[194:197], v198 offset:21504
	ds_read_b128 v[200:203], v198 offset:22528
	ds_read_b128 v[204:207], v198 offset:23552
	global_load_lds_dwordx4 v[208:209], off
	s_add_i32 m0, s7, 0x2000
	s_add_u32 vcc_lo, s30, 0x100000
	v_lshl_add_u64 v[210:211], s[30:31], 0, v[158:159]
	s_addc_u32 vcc_hi, s31, 0
	s_add_i32 s6, s6, s38
	global_load_lds_dwordx4 v[210:211], off
	v_lshl_add_u64 v[212:213], vcc, 0, v[162:163]
	s_mov_b32 m0, s6
	v_lshl_add_u64 v[214:215], s[34:35], 0, v[160:161]
	global_load_lds_dwordx4 v[212:213], off
	v_lshl_add_u64 v[212:213], vcc, 0, v[158:159]
	s_add_i32 m0, s6, 0x2000
	s_nop 0
	global_load_lds_dwordx4 v[212:213], off
	v_lshl_add_u64 v[212:213], s[34:35], 0, v[164:165]
	s_mov_b32 m0, s39
	s_nop 0
	global_load_lds_dwordx4 v[212:213], off
	s_mov_b32 m0, s46
	s_nop 0
	global_load_lds_dwordx4 v[214:215], off
	s_waitcnt vmcnt(8)
	s_waitcnt lgkmcnt(0)
	s_barrier
; #define PG8_STAGE(bufoff, gbase, voff) do { _Pragma("unroll") for (int _i = 0; _i < 2; ++_i) \
;         __builtin_amdgcn_global_load_lds((const unsigned*)((const char*)(gbase) + (voff)[_i]), (LAS unsigned*)(lds + (bufoff) + ldsw + _i * 8192), 16, 0, 0); } while (0)
; #define PG8_LDA(dst, b, h) do { _Pragma("unroll") for (int m = 0; m < 4; ++m) _Pragma("unroll") for (int k = 0; k < 2; ++k) dst[m][k] = *(const LAS bf16x8*)(lds + PG8_SA(b, h) + aoff + m * 2048 + k * 1024); } while (0)
; #define PG8_LDB(dst, b, h) do { _Pragma("unroll") for (int n = 0; n < 2; ++n) _Pragma("unroll") for (int k = 0; k < 2; ++k) dst[n][k] = *(const LAS bf16x8*)(lds + PG8_SB(b, h) + boff + n * 2048 + k * 1024); } while (0)
; #define PG8_MMA(ai, bj, At, Bt) do { __builtin_amdgcn_s_setprio(1); _Pragma("unroll") for (int m = 0; m < 4; ++m) _Pragma("unroll") for (int n = 0; n < 2; ++n) _Pragma("unroll") for (int k = 0; k < 2; ++k) \
;         acc[ai][bj][m][n] = __builtin_amdgcn_mfma_f32_16x16x32_bf16(Bt[n][k], At[m][k], acc[ai][bj][m][n], 0, 0, 0); __builtin_amdgcn_s_setprio(0); } while (0)
; #define PG8_WAIT_V(n) asm volatile("s_waitcnt vmcnt(" #n ")" ::: "memory")
; #define PG8_WAIT_L(n) asm volatile("s_waitcnt lgkmcnt(" #n ")" ::: "memory")
; #define PG8_BAR __builtin_amdgcn_s_barrier()
; #define PG8_SCHED __builtin_amdgcn_sched_barrier(0)
; template <class Epi, class Sched, bool ALIGN_EPI>
; __device__ __forceinline__ void gemm_phase(LAS unsigned char* lds, const Gemm g, const Sched& S, const Epi& E, int wave_s) {
;     ...
;             PG8_WAIT_V(8); PG8_WAIT_L(0); PG8_BAR; PG8_MMA(1, 0, At, B0); PG8_MMA(1, 1, At, B1); PG8_BAR; PG8_SCHED;
;             PG8_LDB(B0, 1, 0); PG8_LDB(B1, 1, 1); PG8_SCHED; PG8_LDA(At, 1, 0); PG8_STAGE(PG8_SA(0, 1), a2 + hstepA, voffA);
;             PG8_WAIT_V(8); PG8_WAIT_L(0); PG8_BAR; PG8_MMA(0, 0, At, B0); PG8_MMA(0, 1, At, B1); PG8_BAR; PG8_SCHED;
	s_setprio 1
	s_waitcnt lgkmcnt(0)
	v_mfma_f32_16x16x32_bf16 v[62:65], v[66:69], v[174:177], v[62:65]
	v_mfma_f32_16x16x32_bf16 v[58:61], v[74:77], v[174:177], v[58:61]
	v_mfma_f32_16x16x32_bf16 v[46:49], v[66:69], v[182:185], v[46:49]
	v_mfma_f32_16x16x32_bf16 v[42:45], v[74:77], v[182:185], v[42:45]
	v_mfma_f32_16x16x32_bf16 v[30:33], v[66:69], v[190:193], v[30:33]
	v_mfma_f32_16x16x32_bf16 v[26:29], v[74:77], v[190:193], v[26:29]
	v_mfma_f32_16x16x32_bf16 v[14:17], v[66:69], v[200:203], v[14:17]
	v_mfma_f32_16x16x32_bf16 v[10:13], v[74:77], v[200:203], v[10:13]
	v_mfma_f32_16x16x32_bf16 v[62:65], v[70:73], v[178:181], v[62:65]
	v_mfma_f32_16x16x32_bf16 v[58:61], v[78:81], v[178:181], v[58:61]
	v_mfma_f32_16x16x32_bf16 v[46:49], v[70:73], v[186:189], v[46:49]
	v_mfma_f32_16x16x32_bf16 v[42:45], v[78:81], v[186:189], v[42:45]
	v_mfma_f32_16x16x32_bf16 v[30:33], v[70:73], v[194:197], v[30:33]
	v_mfma_f32_16x16x32_bf16 v[26:29], v[78:81], v[194:197], v[26:29]
	v_mfma_f32_16x16x32_bf16 v[14:17], v[70:73], v[204:207], v[14:17]
	v_mfma_f32_16x16x32_bf16 v[10:13], v[78:81], v[204:207], v[10:13]
	s_setprio 0
	s_setprio 1
	v_mfma_f32_16x16x32_bf16 v[54:57], v[146:149], v[174:177], v[54:57]
	v_mfma_f32_16x16x32_bf16 v[50:53], v[154:157], v[174:177], v[50:53]
	v_mfma_f32_16x16x32_bf16 v[38:41], v[146:149], v[182:185], v[38:41]
	v_mfma_f32_16x16x32_bf16 v[34:37], v[154:157], v[182:185], v[34:37]
	v_mfma_f32_16x16x32_bf16 v[22:25], v[146:149], v[190:193], v[22:25]
	v_mfma_f32_16x16x32_bf16 v[18:21], v[154:157], v[190:193], v[18:21]
	v_mfma_f32_16x16x32_bf16 v[6:9], v[146:149], v[200:203], v[6:9]
	v_mfma_f32_16x16x32_bf16 v[2:5], v[154:157], v[200:203], v[2:5]
	v_mfma_f32_16x16x32_bf16 v[54:57], v[150:153], v[178:181], v[54:57]
	v_mfma_f32_16x16x32_bf16 v[50:53], v[170:173], v[178:181], v[50:53]
	v_mfma_f32_16x16x32_bf16 v[38:41], v[150:153], v[186:189], v[38:41]
	v_mfma_f32_16x16x32_bf16 v[34:37], v[170:173], v[186:189], v[34:37]
	v_mfma_f32_16x16x32_bf16 v[22:25], v[150:153], v[194:197], v[22:25]
	v_mfma_f32_16x16x32_bf16 v[18:21], v[170:173], v[194:197], v[18:21]
	v_mfma_f32_16x16x32_bf16 v[6:9], v[150:153], v[204:207], v[6:9]
	v_mfma_f32_16x16x32_bf16 v[2:5], v[170:173], v[204:207], v[2:5]
	s_setprio 0
	s_barrier
	s_add_i32 s6, 0, 0x18000
	s_add_i32 s7, 0, 0x1c000
	v_add_u32_e32 v78, s6, v1
	v_add_u32_e32 v170, s7, v1
	ds_read_b128 v[66:69], v78
	ds_read_b128 v[70:73], v78 offset:1024
	ds_read_b128 v[74:77], v78 offset:2048
	ds_read_b128 v[78:81], v78 offset:3072
	ds_read_b128 v[146:149], v170
	ds_read_b128 v[150:153], v170 offset:1024
	ds_read_b128 v[154:157], v170 offset:2048
	ds_read_b128 v[170:173], v170 offset:3072
	s_add_u32 s34, s34, 0x100000
	s_addc_u32 s35, s35, 0
	s_mov_b32 m0, s47
	v_lshl_add_u64 v[216:217], s[34:35], 0, v[164:165]
	ds_read_b128 v[174:177], v198 offset:32768
	ds_read_b128 v[178:181], v198 offset:33792
	ds_read_b128 v[182:185], v198 offset:34816
	ds_read_b128 v[186:189], v198 offset:35840
	ds_read_b128 v[190:193], v198 offset:36864
	ds_read_b128 v[194:197], v198 offset:37888
	ds_read_b128 v[200:203], v198 offset:38912
	ds_read_b128 v[204:207], v198 offset:39936
	global_load_lds_dwordx4 v[216:217], off
	v_lshl_add_u64 v[216:217], s[34:35], 0, v[160:161]
	s_mov_b32 m0, s48
	s_nop 0
	global_load_lds_dwordx4 v[216:217], off
	s_waitcnt vmcnt(8)
	s_waitcnt lgkmcnt(0)
	s_barrier
	s_setprio 1
	s_waitcnt lgkmcnt(0)
	v_mfma_f32_16x16x32_bf16 v[142:145], v[66:69], v[174:177], v[142:145]
	v_mfma_f32_16x16x32_bf16 v[138:141], v[74:77], v[174:177], v[138:141]
	v_mfma_f32_16x16x32_bf16 v[126:129], v[66:69], v[182:185], v[126:129]
	v_mfma_f32_16x16x32_bf16 v[122:125], v[74:77], v[182:185], v[122:125]
	v_mfma_f32_16x16x32_bf16 v[110:113], v[66:69], v[190:193], v[110:113]
	v_mfma_f32_16x16x32_bf16 v[106:109], v[74:77], v[190:193], v[106:109]
	v_mfma_f32_16x16x32_bf16 v[94:97], v[66:69], v[200:203], v[94:97]
	v_mfma_f32_16x16x32_bf16 v[90:93], v[74:77], v[200:203], v[90:93]
	v_mfma_f32_16x16x32_bf16 v[142:145], v[70:73], v[178:181], v[142:145]
	v_mfma_f32_16x16x32_bf16 v[138:141], v[78:81], v[178:181], v[138:141]
	v_mfma_f32_16x16x32_bf16 v[126:129], v[70:73], v[186:189], v[126:129]
	v_mfma_f32_16x16x32_bf16 v[122:125], v[78:81], v[186:189], v[122:125]
	v_mfma_f32_16x16x32_bf16 v[110:113], v[70:73], v[194:197], v[110:113]
	v_mfma_f32_16x16x32_bf16 v[106:109], v[78:81], v[194:197], v[106:109]
	v_mfma_f32_16x16x32_bf16 v[94:97], v[70:73], v[204:207], v[94:97]
	v_mfma_f32_16x16x32_bf16 v[90:93], v[78:81], v[204:207], v[90:93]
	s_setprio 0
	s_setprio 1
	v_mfma_f32_16x16x32_bf16 v[134:137], v[146:149], v[174:177], v[134:137]
	v_mfma_f32_16x16x32_bf16 v[130:133], v[154:157], v[174:177], v[130:133]
	v_mfma_f32_16x16x32_bf16 v[118:121], v[146:149], v[182:185], v[118:121]
	v_mfma_f32_16x16x32_bf16 v[114:117], v[154:157], v[182:185], v[114:117]
	v_mfma_f32_16x16x32_bf16 v[102:105], v[146:149], v[190:193], v[102:105]
	v_mfma_f32_16x16x32_bf16 v[98:101], v[154:157], v[190:193], v[98:101]
	v_mfma_f32_16x16x32_bf16 v[86:89], v[146:149], v[200:203], v[86:89]
	v_mfma_f32_16x16x32_bf16 v[82:85], v[154:157], v[200:203], v[82:85]
	v_mfma_f32_16x16x32_bf16 v[134:137], v[150:153], v[178:181], v[134:137]
	v_mfma_f32_16x16x32_bf16 v[130:133], v[170:173], v[178:181], v[130:133]
	v_mfma_f32_16x16x32_bf16 v[118:121], v[150:153], v[186:189], v[118:121]
	v_mfma_f32_16x16x32_bf16 v[114:117], v[170:173], v[186:189], v[114:117]
	v_mfma_f32_16x16x32_bf16 v[102:105], v[150:153], v[194:197], v[102:105]
	v_mfma_f32_16x16x32_bf16 v[98:101], v[170:173], v[194:197], v[98:101]
	v_mfma_f32_16x16x32_bf16 v[86:89], v[150:153], v[204:207], v[86:89]
	v_mfma_f32_16x16x32_bf16 v[82:85], v[170:173], v[204:207], v[82:85]
	s_setprio 0
	s_barrier
; #define PG8_STAGE(bufoff, gbase, voff) do { _Pragma("unroll") for (int _i = 0; _i < 2; ++_i) \
;         __builtin_amdgcn_global_load_lds((const unsigned*)((const char*)(gbase) + (voff)[_i]), (LAS unsigned*)(lds + (bufoff) + ldsw + _i * 8192), 16, 0, 0); } while (0)
; #define PG8_LDA(dst, b, h) do { _Pragma("unroll") for (int m = 0; m < 4; ++m) _Pragma("unroll") for (int k = 0; k < 2; ++k) dst[m][k] = *(const LAS bf16x8*)(lds + PG8_SA(b, h) + aoff + m * 2048 + k * 1024); } while (0)
; #define PG8_MMA(ai, bj, At, Bt) do { __builtin_amdgcn_s_setprio(1); _Pragma("unroll") for (int m = 0; m < 4; ++m) _Pragma("unroll") for (int n = 0; n < 2; ++n) _Pragma("unroll") for (int k = 0; k < 2; ++k) \
;         acc[ai][bj][m][n] = __builtin_amdgcn_mfma_f32_16x16x32_bf16(Bt[n][k], At[m][k], acc[ai][bj][m][n], 0, 0, 0); __builtin_amdgcn_s_setprio(0); } while (0)
; #define PG8_WAIT_V(n) asm volatile("s_waitcnt vmcnt(" #n ")" ::: "memory")
; #define PG8_WAIT_L(n) asm volatile("s_waitcnt lgkmcnt(" #n ")" ::: "memory")
; #define PG8_BAR __builtin_amdgcn_s_barrier()
; #define PG8_SCHED __builtin_amdgcn_sched_barrier(0)
; template <class Epi, class Sched, bool ALIGN_EPI>
; __device__ __forceinline__ void gemm_phase(LAS unsigned char* lds, const Gemm g, const Sched& S, const Epi& E, int wave_s) {
;     ...
;         for (int t = 0; t < nt; t += 2) {
;             const bool last = (t == nt - 2);
;             const char* a1 = cA + (size_t)(t + 1) * kstep;
;             const char* a2 = last ? nA : cA + (size_t)(t + 2) * kstep; const char* b2 = last ? nB : cB + (size_t)(t + 2) * kstep;
;             const char* a3 = a2 + kstep; const char* b3 = b2 + kstep;
;     ...
;             PG8_WAIT_V(8); PG8_WAIT_L(0); PG8_BAR; PG8_MMA(0, 0, At, B0); PG8_MMA(0, 1, At, B1); PG8_BAR; PG8_SCHED;
;             PG8_LDA(At, 1, 1); PG8_STAGE(PG8_SB(1, 0), b3, voffB); PG8_STAGE(PG8_SB(1, 1), b3 + hstepB, voffB); PG8_STAGE(PG8_SA(1, 0), a3, voffA);
;             PG8_WAIT_V(8); PG8_WAIT_L(0); PG8_BAR; PG8_MMA(1, 0, At, B0); PG8_MMA(1, 1, At, B1); PG8_BAR; PG8_SCHED;
	s_add_i32 s6, s6, s38
	v_lshl_add_u64 v[208:209], v[208:209], 0, s[74:75]
	s_mov_b32 m0, s6
	ds_read_b128 v[174:177], v198 offset:49152
	ds_read_b128 v[178:181], v198 offset:50176
	ds_read_b128 v[182:185], v198 offset:51200
	ds_read_b128 v[186:189], v198 offset:52224
	ds_read_b128 v[190:193], v198 offset:53248
	ds_read_b128 v[194:197], v198 offset:54272
	ds_read_b128 v[200:203], v198 offset:55296
	ds_read_b128 v[204:207], v198 offset:56320
	global_load_lds_dwordx4 v[208:209], off
	s_add_i32 m0, s6, 0x2000
	s_add_u32 s30, s30, 0x100080
	v_lshl_add_u64 v[208:209], v[210:211], 0, s[74:75]
	s_addc_u32 s31, s31, 0
	s_add_i32 s6, s7, s38
	global_load_lds_dwordx4 v[208:209], off
	v_lshl_add_u64 v[208:209], s[30:31], 0, v[162:163]
	s_mov_b32 m0, s6
	s_nop 0
	global_load_lds_dwordx4 v[208:209], off
	v_lshl_add_u64 v[208:209], s[30:31], 0, v[158:159]
	s_add_i32 m0, s6, 0x2000
	s_nop 0
	global_load_lds_dwordx4 v[208:209], off
	v_lshl_add_u64 v[208:209], v[212:213], 0, s[74:75]
	s_mov_b32 m0, s85
	s_nop 0
	global_load_lds_dwordx4 v[208:209], off
	v_lshl_add_u64 v[208:209], v[214:215], 0, s[74:75]
	s_mov_b32 m0, s86
	s_nop 0
	global_load_lds_dwordx4 v[208:209], off
	s_waitcnt vmcnt(8)
	s_waitcnt lgkmcnt(0)
	s_barrier
	s_setprio 1
	s_waitcnt lgkmcnt(0)
	v_mfma_f32_16x16x32_bf16 v[62:65], v[66:69], v[174:177], v[62:65]
	v_mfma_f32_16x16x32_bf16 v[58:61], v[74:77], v[174:177], v[58:61]
	v_mfma_f32_16x16x32_bf16 v[46:49], v[66:69], v[182:185], v[46:49]
	v_mfma_f32_16x16x32_bf16 v[42:45], v[74:77], v[182:185], v[42:45]
	v_mfma_f32_16x16x32_bf16 v[30:33], v[66:69], v[190:193], v[30:33]
	v_mfma_f32_16x16x32_bf16 v[26:29], v[74:77], v[190:193], v[26:29]
	v_mfma_f32_16x16x32_bf16 v[14:17], v[66:69], v[200:203], v[14:17]
	v_mfma_f32_16x16x32_bf16 v[10:13], v[74:77], v[200:203], v[10:13]
	v_mfma_f32_16x16x32_bf16 v[62:65], v[70:73], v[178:181], v[62:65]
	v_mfma_f32_16x16x32_bf16 v[58:61], v[78:81], v[178:181], v[58:61]
	v_mfma_f32_16x16x32_bf16 v[46:49], v[70:73], v[186:189], v[46:49]
	v_mfma_f32_16x16x32_bf16 v[42:45], v[78:81], v[186:189], v[42:45]
	v_mfma_f32_16x16x32_bf16 v[30:33], v[70:73], v[194:197], v[30:33]
	v_mfma_f32_16x16x32_bf16 v[26:29], v[78:81], v[194:197], v[26:29]
	v_mfma_f32_16x16x32_bf16 v[14:17], v[70:73], v[204:207], v[14:17]
	v_mfma_f32_16x16x32_bf16 v[10:13], v[78:81], v[204:207], v[10:13]
	s_setprio 0
	s_setprio 1
	v_mfma_f32_16x16x32_bf16 v[54:57], v[146:149], v[174:177], v[54:57]
	v_mfma_f32_16x16x32_bf16 v[50:53], v[154:157], v[174:177], v[50:53]
	v_mfma_f32_16x16x32_bf16 v[38:41], v[146:149], v[182:185], v[38:41]
	v_mfma_f32_16x16x32_bf16 v[34:37], v[154:157], v[182:185], v[34:37]
	v_mfma_f32_16x16x32_bf16 v[22:25], v[146:149], v[190:193], v[22:25]
	v_mfma_f32_16x16x32_bf16 v[18:21], v[154:157], v[190:193], v[18:21]
	v_mfma_f32_16x16x32_bf16 v[6:9], v[146:149], v[200:203], v[6:9]
	v_mfma_f32_16x16x32_bf16 v[2:5], v[154:157], v[200:203], v[2:5]
	v_mfma_f32_16x16x32_bf16 v[54:57], v[150:153], v[178:181], v[54:57]
	v_mfma_f32_16x16x32_bf16 v[50:53], v[170:173], v[178:181], v[50:53]
	v_mfma_f32_16x16x32_bf16 v[38:41], v[150:153], v[186:189], v[38:41]
	v_mfma_f32_16x16x32_bf16 v[34:37], v[170:173], v[186:189], v[34:37]
	v_mfma_f32_16x16x32_bf16 v[22:25], v[150:153], v[194:197], v[22:25]
	v_mfma_f32_16x16x32_bf16 v[18:21], v[170:173], v[194:197], v[18:21]
	v_mfma_f32_16x16x32_bf16 v[6:9], v[150:153], v[204:207], v[6:9]
	v_mfma_f32_16x16x32_bf16 v[2:5], v[170:173], v[204:207], v[2:5]
	s_setprio 0
	s_add_i32 s94, s94, 2
	s_add_u32 s10, s10, 0x100
	s_addc_u32 s11, s11, 0
	s_add_u32 s92, s92, 0x100
	s_addc_u32 s93, s93, 0
	s_cmp_gt_u32 s94, 61
	s_cbranch_scc1 .Lgemm_mlpdn_exit
	s_add_u32 s30, s10, 0xfff00080
	s_addc_u32 s31, s11, -1
	s_add_i32 s95, 0, 0x10000
	s_cmp_eq_u32 s94, 60
	s_cselect_b32 s35, s25, s31
	s_cselect_b32 s34, s90, s30
	s_cselect_b32 s31, s23, s93
	s_cselect_b32 s30, s91, s92
	s_add_i32 s6, 0, 0x14000
	v_add_u32_e32 v78, s95, v1
	v_add_u32_e32 v170, s6, v1
	s_barrier
	s_branch .Lgemm_mlpdn_head
.Lgemm_mlpdn_exit:
	s_barrier
	s_and_b64 vcc, exec, s[18:19]
	s_cbranch_vccz .LBB0_1559
	s_barrier
